# v27 with the prep2 pre-pass length varied per workgroup (1/3/5/7 items) to spread the tile-boundary store bursts
# baseline (speedup 1.0000x reference)
.LBB0_361:
	s_andn2_b64 vcc, exec, s[0:1]
	s_cbranch_vccnz .LBB0_6
	s_add_u32 s18, s62, 0x800000
	s_addc_u32 s19, s63, 0
	v_readlane_b32 s0, v255, 30
	s_cmp_lt_i32 s0, 1
	s_mov_b64 s[0:1], -1
	s_cbranch_scc1 .LBB0_417
	v_readlane_b32 s0, v255, 30
	s_cmp_gt_i32 s0, 1
	s_mov_b64 s[0:1], -1
	s_cbranch_scc0 .LBB0_409
	v_readlane_b32 s82, v253, 0
	s_lshr_b32 s82, s82, 3
	s_and_b32 s82, s82, 3
	s_lshl_b32 s82, s82, 1
	s_add_i32 s82, s82, 1
	s_lshl_b32 s82, s82, 7
	s_add_i32 s82, s82, -1
	s_mov_b32 s83, 1
	v_readlane_b32 s78, v255, 28
	v_readlane_b32 s79, v255, 29
	s_nop 4
	s_branch .Lp2_prep2
